# m11 + FFN-up and in-proj unit prologues: the scalar tile-order chain interleaved one-to-one with the 64 zeroing moves (VALU of one wave issues beside SALU of the other)
# baseline (speedup 1.0000x reference)
.Lzs_a:
	v_mov_b64_e32 v[4:5], 0
	v_mov_b64_e32 v[6:7], 0
	v_mov_b64_e32 v[8:9], 0
	v_mov_b64_e32 v[10:11], 0
	v_mov_b64_e32 v[12:13], 0
	v_mov_b64_e32 v[14:15], 0
	v_mov_b64_e32 v[16:17], 0
	v_mov_b64_e32 v[18:19], 0
	v_mov_b64_e32 v[20:21], 0
	v_mov_b64_e32 v[22:23], 0
	v_mov_b64_e32 v[24:25], 0
	v_mov_b64_e32 v[26:27], 0
	v_mov_b64_e32 v[28:29], 0
	v_mov_b64_e32 v[30:31], 0
	v_mov_b64_e32 v[32:33], 0
	v_mov_b64_e32 v[34:35], 0
	v_mov_b64_e32 v[36:37], 0
	v_mov_b64_e32 v[38:39], 0
	v_mov_b64_e32 v[40:41], 0
	v_mov_b64_e32 v[42:43], 0
	v_mov_b64_e32 v[44:45], 0
	v_mov_b64_e32 v[46:47], 0
	v_mov_b64_e32 v[48:49], 0
	v_mov_b64_e32 v[50:51], 0
	v_mov_b64_e32 v[52:53], 0
	v_mov_b64_e32 v[54:55], 0
	v_mov_b64_e32 v[56:57], 0
	v_mov_b64_e32 v[58:59], 0
	v_mov_b64_e32 v[60:61], 0
	v_mov_b64_e32 v[62:63], 0
	v_mov_b64_e32 v[64:65], 0
	v_mov_b64_e32 v[66:67], 0
	v_mov_b64_e32 v[68:69], 0
	v_mov_b64_e32 v[70:71], 0
	v_mov_b64_e32 v[72:73], 0
	v_mov_b64_e32 v[74:75], 0
	v_mov_b64_e32 v[76:77], 0
	v_mov_b64_e32 v[78:79], 0
	v_mov_b64_e32 v[80:81], 0
	v_mov_b64_e32 v[82:83], 0
	v_mov_b64_e32 v[84:85], 0
	v_mov_b64_e32 v[86:87], 0
	v_mov_b64_e32 v[88:89], 0
	v_mov_b64_e32 v[90:91], 0
	v_mov_b64_e32 v[92:93], 0
	v_mov_b64_e32 v[94:95], 0
	v_mov_b64_e32 v[96:97], 0
	v_mov_b64_e32 v[98:99], 0
	v_mov_b64_e32 v[100:101], 0
	v_mov_b64_e32 v[102:103], 0
	v_mov_b64_e32 v[104:105], 0
	v_mov_b64_e32 v[106:107], 0
	v_mov_b64_e32 v[108:109], 0
	v_mov_b64_e32 v[110:111], 0
	v_mov_b64_e32 v[112:113], 0
	v_mov_b64_e32 v[114:115], 0
	v_mov_b64_e32 v[116:117], 0
	v_mov_b64_e32 v[118:119], 0
	v_mov_b64_e32 v[120:121], 0
	v_mov_b64_e32 v[122:123], 0
	v_mov_b64_e32 v[124:125], 0
	s_branch .LBB0_418

.LBB0_416:
	s_add_i32 s25, s25, 1
	s_mul_i32 s10, s25, s95
	s_mul_hi_u32 s11, s25, s94
	s_add_i32 s11, s11, s10
	s_mul_i32 s10, s25, s94
	s_add_u32 s10, s10, s2
	s_addc_u32 s11, s11, s33
	v_mov_b64_e32 v[2:3], 0x580
	v_cmp_lt_i64_e64 s[38:39], s[10:11], v[2:3]
	v_mov_b64_e32 v[2:3], 0x57f
	v_cmp_gt_i64_e32 vcc, s[10:11], v[2:3]
	s_cbranch_vccnz .Lzs_a
	s_ashr_i32 s11, s10, 31
	v_mov_b64_e32 v[4:5], 0
	s_lshr_b32 s11, s11, 29
	v_mov_b64_e32 v[6:7], 0
	s_add_i32 s11, s10, s11
	v_mov_b64_e32 v[8:9], 0
	s_ashr_i32 s34, s11, 3
	v_mov_b64_e32 v[10:11], 0
	s_and_b32 s11, s11, -8
	v_mov_b64_e32 v[12:13], 0
	s_sub_i32 s10, s10, s11
	v_mov_b64_e32 v[14:15], 0
	s_cmp_lt_i32 s10, 0
	v_mov_b64_e32 v[16:17], 0
	s_movk_i32 s11, 0xb1
	v_mov_b64_e32 v[18:19], 0
	s_cselect_b32 s11, s11, 0xb0
	v_mov_b64_e32 v[20:21], 0
	s_mul_i32 s10, s10, s11
	v_mov_b64_e32 v[22:23], 0
	s_add_i32 s10, s10, s34
	v_mov_b64_e32 v[24:25], 0
	s_mul_hi_i32 s11, s10, 0x2e8ba2e9
	v_mov_b64_e32 v[26:27], 0
	s_lshr_b32 s34, s11, 31
	v_mov_b64_e32 v[28:29], 0
	s_ashr_i32 s11, s11, 5
	v_mov_b64_e32 v[30:31], 0
	s_add_i32 s11, s11, s34
	v_mov_b64_e32 v[32:33], 0
	s_lshl_b32 s34, s11, 3
	v_mov_b64_e32 v[34:35], 0
	s_sub_i32 s35, 64, s34
	v_mov_b64_e32 v[36:37], 0
	s_min_i32 s35, s35, 8
	v_mov_b64_e32 v[38:39], 0
	s_abs_i32 s36, s35
	v_mov_b64_e32 v[40:41], 0
	v_cvt_f32_u32_e32 v2, s36
	v_mov_b64_e32 v[42:43], 0
	s_sub_i32 s48, 0, s36
	v_mov_b64_e32 v[44:45], 0
	s_mulk_i32 s11, 0xb0
	v_mov_b64_e32 v[46:47], 0
	s_sub_i32 s10, s10, s11
	v_mov_b64_e32 v[48:49], 0
	v_rcp_iflag_f32_e32 v2, v2
	v_mov_b64_e32 v[50:51], 0
	s_abs_i32 s11, s10
	v_mov_b64_e32 v[52:53], 0
	s_xor_b32 s37, s10, s35
	v_mov_b64_e32 v[54:55], 0
	s_ashr_i32 s37, s37, 31
	v_mov_b64_e32 v[56:57], 0
	v_mul_f32_e32 v2, 0x4f7ffffe, v2
	v_mov_b64_e32 v[58:59], 0
	v_cvt_u32_f32_e32 v2, v2
	v_mov_b64_e32 v[60:61], 0
	s_nop 0
	v_mov_b64_e32 v[62:63], 0
	v_readfirstlane_b32 s49, v2
	v_mov_b64_e32 v[64:65], 0
	s_mul_i32 s48, s48, s49
	v_mov_b64_e32 v[66:67], 0
	s_mul_hi_u32 s48, s49, s48
	v_mov_b64_e32 v[68:69], 0
	s_add_i32 s49, s49, s48
	v_mov_b64_e32 v[70:71], 0
	s_mul_hi_u32 s48, s11, s49
	v_mov_b64_e32 v[72:73], 0
	s_mul_i32 s49, s48, s36
	v_mov_b64_e32 v[74:75], 0
	s_sub_i32 s11, s11, s49
	v_mov_b64_e32 v[76:77], 0
	s_add_i32 s50, s48, 1
	v_mov_b64_e32 v[78:79], 0
	s_sub_i32 s49, s11, s36
	v_mov_b64_e32 v[80:81], 0
	s_cmp_ge_u32 s11, s36
	v_mov_b64_e32 v[82:83], 0
	s_cselect_b32 s48, s50, s48
	v_mov_b64_e32 v[84:85], 0
	s_cselect_b32 s11, s49, s11
	v_mov_b64_e32 v[86:87], 0
	s_add_i32 s49, s48, 1
	v_mov_b64_e32 v[88:89], 0
	s_cmp_ge_u32 s11, s36
	v_mov_b64_e32 v[90:91], 0
	s_cselect_b32 s11, s49, s48
	v_mov_b64_e32 v[92:93], 0
	s_xor_b32 s11, s11, s37
	v_mov_b64_e32 v[94:95], 0
	s_sub_i32 s48, s11, s37
	v_mov_b64_e32 v[96:97], 0
	s_mul_i32 s11, s48, s35
	v_mov_b64_e32 v[98:99], 0
	s_sub_i32 s10, s10, s11
	v_mov_b64_e32 v[100:101], 0
	s_add_i32 s34, s34, s10
	v_mov_b64_e32 v[102:103], 0
	s_and_b32 s11, s34, -16
	v_mov_b64_e32 v[104:105], 0
	s_bitcmp0_b32 s34, 3
	v_mov_b64_e32 v[106:107], 0
	s_cselect_b32 s34, s88, 0x6521
	v_mov_b64_e32 v[108:109], 0
	s_lshl_b32 s35, s10, 1
	v_mov_b64_e32 v[110:111], 0
	s_and_b32 s35, s35, 12
	v_mov_b64_e32 v[112:113], 0
	s_lshr_b32 s34, s34, s35
	v_mov_b64_e32 v[114:115], 0
	s_and_b32 s34, s34, 7
	v_mov_b64_e32 v[116:117], 0
	s_and_b32 s10, s10, 1
	v_mov_b64_e32 v[118:119], 0
	s_xor_b32 s35, s34, 15
	v_mov_b64_e32 v[120:121], 0
	s_cmp_eq_u32 s10, 0
	v_mov_b64_e32 v[122:123], 0
	s_cselect_b32 s10, s34, s35
	v_mov_b64_e32 v[124:125], 0
	s_or_b32 s50, s10, s11
.LBB0_418:
	s_ashr_i32 s51, s50, 31
	v_mov_b64_e32 v[126:127], 0
	s_lshl_b64 s[10:11], s[50:51], 19
	v_mov_b64_e32 v[128:129], 0
	s_add_u32 s52, s12, s10
	s_addc_u32 s53, s13, s11
	s_and_b64 s[10:11], s[38:39], exec
	s_cselect_b32 s34, s53, s9
	s_cselect_b32 s35, s52, s8
	s_ashr_i32 s49, s48, 31
	s_lshl_b64 s[10:11], s[48:49], 19
	s_add_u32 s56, s14, s10
	s_addc_u32 s57, s15, s11
	s_and_b64 s[10:11], s[38:39], exec
	s_cselect_b32 s36, s57, s1
	s_cselect_b32 s37, s56, s0
	s_add_u32 s49, s0, 0x100
	s_addc_u32 s51, s1, 0
	s_add_u32 s0, s8, 0x40080
	v_mov_b64_e32 v[2:3], 0
	s_addc_u32 s1, s9, 0
	s_mov_b32 s55, -2

.LBB0_793:
	s_add_i32 s29, s29, 1
	s_mul_i32 s10, s29, s95
	s_mul_hi_u32 s11, s29, s94
	s_add_i32 s11, s11, s10
	s_mul_i32 s10, s29, s94
	s_add_u32 s10, s10, s2
	s_addc_u32 s11, s11, s33
	v_cmp_gt_i64_e32 vcc, s[10:11], v[198:199]
	v_cmp_lt_i64_e64 s[40:41], s[10:11], v[196:197]
	s_cbranch_vccnz .Lzs_b
	s_ashr_i32 s11, s10, 31
	v_mov_b64_e32 v[4:5], 0
	s_lshr_b32 s11, s11, 29
	v_mov_b64_e32 v[6:7], 0
	s_add_i32 s11, s10, s11
	v_mov_b64_e32 v[8:9], 0
	s_ashr_i32 s36, s11, 3
	v_mov_b64_e32 v[10:11], 0
	s_and_b32 s11, s11, -8
	v_mov_b64_e32 v[12:13], 0
	s_sub_i32 s10, s10, s11
	v_mov_b64_e32 v[14:15], 0
	s_cmp_lt_i32 s10, 0
	v_mov_b64_e32 v[16:17], 0
	s_movk_i32 s11, 0x99
	v_mov_b64_e32 v[18:19], 0
	s_cselect_b32 s11, s11, 0x98
	v_mov_b64_e32 v[20:21], 0
	s_mul_i32 s10, s10, s11
	v_mov_b64_e32 v[22:23], 0
	s_add_i32 s10, s10, s36
	v_mov_b64_e32 v[24:25], 0
	s_mul_hi_i32 s11, s10, 0x6bca1af3
	v_mov_b64_e32 v[26:27], 0
	s_lshr_b32 s36, s11, 31
	v_mov_b64_e32 v[28:29], 0
	s_ashr_i32 s11, s11, 6
	v_mov_b64_e32 v[30:31], 0
	s_add_i32 s11, s11, s36
	v_mov_b64_e32 v[32:33], 0
	s_lshl_b32 s36, s11, 3
	v_mov_b64_e32 v[34:35], 0
	s_sub_i32 s37, 64, s36
	v_mov_b64_e32 v[36:37], 0
	s_min_i32 s37, s37, 8
	v_mov_b64_e32 v[38:39], 0
	s_abs_i32 s42, s37
	v_mov_b64_e32 v[40:41], 0
	v_cvt_f32_u32_e32 v2, s42
	v_mov_b64_e32 v[42:43], 0
	s_sub_i32 s52, 0, s42
	v_mov_b64_e32 v[44:45], 0
	s_mulk_i32 s11, 0x98
	v_mov_b64_e32 v[46:47], 0
	s_sub_i32 s10, s10, s11
	v_mov_b64_e32 v[48:49], 0
	v_rcp_iflag_f32_e32 v2, v2
	v_mov_b64_e32 v[50:51], 0
	s_abs_i32 s11, s10
	v_mov_b64_e32 v[52:53], 0
	s_xor_b32 s43, s10, s37
	v_mov_b64_e32 v[54:55], 0
	s_ashr_i32 s43, s43, 31
	v_mov_b64_e32 v[56:57], 0
	v_mul_f32_e32 v2, 0x4f7ffffe, v2
	v_mov_b64_e32 v[58:59], 0
	v_cvt_u32_f32_e32 v2, v2
	v_mov_b64_e32 v[60:61], 0
	s_nop 0
	v_mov_b64_e32 v[62:63], 0
	v_readfirstlane_b32 s53, v2
	v_mov_b64_e32 v[64:65], 0
	s_mul_i32 s52, s52, s53
	v_mov_b64_e32 v[66:67], 0
	s_mul_hi_u32 s52, s53, s52
	v_mov_b64_e32 v[68:69], 0
	s_add_i32 s53, s53, s52
	v_mov_b64_e32 v[70:71], 0
	s_mul_hi_u32 s52, s11, s53
	v_mov_b64_e32 v[72:73], 0
	s_mul_i32 s53, s52, s42
	v_mov_b64_e32 v[74:75], 0
	s_sub_i32 s11, s11, s53
	v_mov_b64_e32 v[76:77], 0
	s_add_i32 s54, s52, 1
	v_mov_b64_e32 v[78:79], 0
	s_sub_i32 s53, s11, s42
	v_mov_b64_e32 v[80:81], 0
	s_cmp_ge_u32 s11, s42
	v_mov_b64_e32 v[82:83], 0
	s_cselect_b32 s52, s54, s52
	v_mov_b64_e32 v[84:85], 0
	s_cselect_b32 s11, s53, s11
	v_mov_b64_e32 v[86:87], 0
	s_add_i32 s53, s52, 1
	v_mov_b64_e32 v[88:89], 0
	s_cmp_ge_u32 s11, s42
	v_mov_b64_e32 v[90:91], 0
	s_cselect_b32 s11, s53, s52
	v_mov_b64_e32 v[92:93], 0
	s_xor_b32 s11, s11, s43
	v_mov_b64_e32 v[94:95], 0
	s_sub_i32 s52, s11, s43
	v_mov_b64_e32 v[96:97], 0
	s_mul_i32 s11, s52, s37
	v_mov_b64_e32 v[98:99], 0
	s_sub_i32 s10, s10, s11
	v_mov_b64_e32 v[100:101], 0
	s_add_i32 s36, s36, s10
	v_mov_b64_e32 v[102:103], 0
	s_and_b32 s11, s36, -16
	v_mov_b64_e32 v[104:105], 0
	s_bitcmp0_b32 s36, 3
	v_mov_b64_e32 v[106:107], 0
	s_cselect_b32 s36, s88, 0x6521
	v_mov_b64_e32 v[108:109], 0
	s_lshl_b32 s37, s10, 1
	v_mov_b64_e32 v[110:111], 0
	s_and_b32 s37, s37, 12
	v_mov_b64_e32 v[112:113], 0
	s_lshr_b32 s36, s36, s37
	v_mov_b64_e32 v[114:115], 0
	s_and_b32 s36, s36, 7
	v_mov_b64_e32 v[116:117], 0
	s_and_b32 s10, s10, 1
	v_mov_b64_e32 v[118:119], 0
	s_xor_b32 s37, s36, 15
	v_mov_b64_e32 v[120:121], 0
	s_cmp_eq_u32 s10, 0
	v_mov_b64_e32 v[122:123], 0
	s_cselect_b32 s10, s36, s37
	v_mov_b64_e32 v[124:125], 0
	s_or_b32 s56, s10, s11
.LBB0_795:
	s_ashr_i32 s57, s56, 31
	v_mov_b64_e32 v[126:127], 0
	s_lshl_b64 s[10:11], s[56:57], 19
	v_mov_b64_e32 v[128:129], 0
	s_add_u32 s58, s12, s10
	s_addc_u32 s59, s13, s11
	s_and_b64 s[10:11], s[40:41], exec
	s_cselect_b32 s36, s59, s9
	s_cselect_b32 s37, s58, s8
	s_ashr_i32 s53, s52, 31
	s_lshl_b64 s[10:11], s[52:53], 19
	s_add_u32 s60, s14, s10
	s_addc_u32 s61, s15, s11
	s_and_b64 s[10:11], s[40:41], exec
	s_cselect_b32 s42, s61, s1
	s_cselect_b32 s43, s60, s0
	s_add_u32 s53, s0, 0x100
	s_addc_u32 s54, s1, 0
	s_add_u32 s0, s8, 0x40080
	v_mov_b64_e32 v[2:3], 0
	s_addc_u32 s1, s9, 0
	s_mov_b32 s55, -2
